# v112 + fox stage loop: the two V pieces of the next stage staged with LDS-DMA (2 ds_write_b128 fewer per wave per stage)
# speedup vs baseline: 1.0144x; 1.0056x over previous
; __device__ __forceinline__ int opaque_tid() { int t = (int)threadIdx.x; asm volatile("" : "+v"(t)); return t; }
; #define LAS __attribute__((address_space(3)))
; __device__ __forceinline__ int opaque_bx() { int b = (int)blockIdx.x; asm volatile("" : "+s"(b)); return b; }
; __device__ __forceinline__ KP kparams() { KP p = (KP)__builtin_amdgcn_kernarg_segment_ptr(); asm volatile("" : "+s"(p)); return p; }
; __device__ __forceinline__ void fox_phase(LAS unsigned char* lds, int L) {
;     constexpr int FK = 0, FV = 18432, FA = FV + 16384, FST = FA + 2048;
;     const KP P = kparams(); const int tid = opaque_tid(), lane = tid & 63, wave = __builtin_amdgcn_readfirstlane(tid >> 6);
;     const int r32 = lane & 31, hi = lane >> 5;
;     const int bx = opaque_bx(), vcu = (bx & 7) * 32 + (bx >> 3), xcd = vcu >> 5, grp = (vcu & 31) >> 2, mi = vcu & 3;
;     unsigned char* ws = P->ws;
;     const bf16* Qb = (const bf16*)(ws + WS_Q); const bf16* Kb = (const bf16*)(ws + WS_K); const bf16* Vb = (const bf16*)(ws + WS_V); bf16* Ob = (bf16*)(ws + WS_O);
;     LAS float* pre = (LAS float*)(lds + OFF_PRE);
;     const int kvs = tid >> 3, ch = tid & 7;
;     const int klds = FK + kvs * 144 + ch * 16;
;     const int vkey0 = 64 * ((2 * wave) >> 3) + 16 * ((2 * wave) & 3) + (lane >> 2), vcol0 = 32 * (((2 * wave) >> 2) & 1) + 8 * (lane & 3);
;     const int vlds = FV + ((2 * wave) >> 3) * 8192 + (((2 * wave) >> 2) & 1) * 4096 + ((2 * wave) & 3) * 1024 + 16 * lane;
.LBB0_211:
	s_and_b64 vcc, exec, s[4:5]
	s_cbranch_vccz .LBB0_266
	s_mov_b64 s[4:5], s[60:61]
	s_waitcnt vmcnt(0)
	v_mov_b32_e32 v133, v197
	s_mov_b32 s7, s57
	v_lshlrev_b32_e32 v167, 4, v133
	v_readfirstlane_b32 s3, v133
	v_bfe_u32 v1, v133, 5, 1
	v_ashrrev_i32_e32 v134, 3, v133
	v_and_b32_e32 v0, 0x70, v167
	s_ashr_i32 s6, s3, 6
	s_load_dwordx2 s[20:21], s[4:5], 0xb0
	v_mad_u64_u32 v[136:137], s[4:5], v134, s67, v[0:1]
	s_lshl_b32 s4, s6, 1
	s_lshl_b32 s8, s7, 5
	s_ashr_i32 s9, s3, 8
	s_and_b32 s10, s4, 2
	s_and_b32 s8, s8, 0xe0
	s_ashr_i32 s7, s7, 3
	s_lshl_b32 s24, s9, 6
	s_lshl_b32 s25, s10, 4
	v_and_b32_e32 v166, 63, v133
	s_or_b32 s4, s25, s24
	v_bfe_u32 v3, v133, 2, 4
	s_add_i32 s8, s8, s7
	s_and_b32 s27, s7, 3
	v_or_b32_e32 v138, s4, v3
	v_lshlrev_b32_e32 v8, 4, v166
	s_ashr_i32 s4, s8, 1
	s_bfe_u32 s26, s7, 0x30002
	s_bfe_u32 s36, s3, 0x10007
	v_lshlrev_b32_e32 v4, 3, v133
	s_and_b32 s28, s4, -16
	s_xor_b32 s29, s27, 7
	v_lshl_or_b32 v9, s9, 13, v8
	v_and_b32_e32 v137, 24, v4
	s_waitcnt lgkmcnt(0)
	s_add_u32 s30, s20, 0x1a800000
	v_lshlrev_b32_e32 v4, 3, v1
	v_lshlrev_b32_e32 v140, 4, v1
	v_mov_b32_e32 v141, v2
	v_lshl_or_b32 v9, s36, 12, v9
	v_lshlrev_b32_e32 v171, 2, v1
	v_lshlrev_b32_e32 v173, 8, v1
	v_lshlrev_b32_e32 v1, 2, v133
	s_addc_u32 s31, s21, 0
	s_lshl_b32 s34, s6, 5
	v_lshl_add_u64 v[6:7], s[20:21], 0, v[140:141]
	v_lshl_or_b32 v141, s10, 10, v9
	v_mov_b32_e32 v9, 0x3f80
	v_readfirstlane_b32 s100, v141
	v_cmp_gt_u32_e32 vcc, 32, v166
	v_and_b32_e32 v174, 0xc0, v8
	v_add_u32_e32 v8, 0xfc, v1
	s_add_i32 s100, s100, 0x4400
	s_cmp_lt_u32 s3, 64
	v_cndmask_b32_e32 v9, 0, v9, vcc
	s_mov_b32 s3, 0x5040100
	v_and_b32_e32 v175, 0xfc, v8
	v_add_u32_e32 v8, 0xf8, v1
	s_cselect_b64 s[16:17], -1, 0
	s_add_u32 s18, s20, 0x1a900000
	v_perm_b32 v96, v9, v9, s3
	s_pack_ll_b32_b16 s3, 0, 0
	v_and_b32_e32 v176, 0xfc, v8
	v_add_u32_e32 v8, 0xf0, v1
	v_add_u32_e32 v1, 0xe0, v1
	s_addc_u32 s19, s21, 0
	v_mov_b32_e32 v98, s3
	v_mov_b32_e32 v99, s3
	v_and_b32_e32 v178, 0xfc, v1
	s_lshl_b32 s3, s26, 7
	v_mov_b32_e32 v1, v2
	s_or_b32 s72, s3, 0x400
	v_lshl_add_u64 v[144:145], s[20:21], 0, v[0:1]
	v_lshl_add_u64 v[0:1], v[144:145], 0, s[72:73]
	s_mov_b64 s[22:23], 0xe400000
	v_lshl_add_u64 v[146:147], v[0:1], 0, s[22:23]
	v_lshlrev_b32_e32 v0, 1, v137
	v_lshl_or_b32 v0, s36, 6, v0
	v_mov_b32_e32 v1, v2
	v_mov_b32_e32 v5, v2
	v_lshl_add_u64 v[148:149], s[20:21], 0, v[0:1]
	v_lshl_add_u64 v[4:5], s[20:21], 0, v[4:5]
	v_lshl_add_u64 v[0:1], v[148:149], 0, s[72:73]
	s_mov_b64 s[20:21], 0x12400000
	v_lshl_add_u64 v[150:151], v[0:1], 0, s[20:21]
	v_lshl_add_u64 v[0:1], v[4:5], 0, s[72:73]
	v_mov_b32_e32 v10, 0x5040100
	v_lshl_add_u64 v[152:153], v[0:1], 0, s[92:93]
	v_or_b32_e32 v0, s24, v3
	v_and_b32_e32 v132, 31, v133
	v_readlane_b32 s1, v254, 1
	v_perm_b32 v97, 0, v9, v10
	v_lshlrev_b32_e32 v9, 1, v133
	v_lshl_add_u64 v[6:7], v[6:7], 0, s[72:73]
	v_or_b32_e32 v154, s25, v0
	v_ashrrev_i32_e32 v135, 31, v134
	v_ashrrev_i32_e32 v139, 31, v138
	v_cmp_gt_i32_e64 s[4:5], s64, v133
	v_cmp_gt_u32_e64 s[6:7], 16, v166
	v_lshl_add_u32 v168, v166, 2, s1
	v_mul_u32_u24_e32 v169, 0x90, v132
	v_lshlrev_b32_e32 v170, 4, v132
	v_and_b32_e32 v172, 32, v9
	s_mov_b32 s35, 0
	v_cmp_eq_u32_e64 s[8:9], 0, v166
	v_cmp_gt_u32_e64 s[10:11], 2, v166
	v_and_b32_e32 v177, 0xfc, v8
	v_cmp_gt_u32_e64 s[12:13], 4, v166
	v_cmp_gt_u32_e64 s[14:15], 8, v166
	v_lshl_add_u64 v[142:143], v[6:7], 0, s[68:69]
	s_mov_b32 s72, s3
	v_ashrrev_i32_e32 v155, 31, v154
	s_branch .LBB0_214

; #define FOX_LOAD(T) do { const bf16* kg = Kb + (tokb + 128 * (T) + kvs) * 1024 + col + 8 * ch; const bf16* vg = Vb + (tokb + 128 * (T) + vkey0) * 1024 + col + vcol0; \
;         kreg[0] = *(const u32x4*)(kg); kreg[1] = *(const u32x4*)(kg + 64 * 1024); vreg[0] = *(const u32x4*)(vg); vreg[1] = *(const u32x4*)(vg + 16 * 1024); \
;         if (tid < 128) creg = clp[128 * (T) + tid] + pre[(T)]; } while (0)
; __device__ __forceinline__ void fox_phase(LAS unsigned char* lds, int L) {
;     ...
;             if (it + 1 < NT) FOX_LOAD(T - 1);
.LBB0_227:
	s_add_i32 s43, s3, 1
	s_cmp_lt_u32 s43, s38
	s_cselect_b64 s[22:23], -1, 0
	s_cmp_ge_u32 s43, s38
	s_cbranch_scc1 .LBB0_231
	s_bitcmp1_b32 s43, 0
	s_cselect_b32 s101, 0x9000, 0
	s_add_i32 s101, s101, s100
	s_add_u32 s44, s72, 0xe400000
	s_addc_u32 s45, s73, 0
	v_lshl_add_u64 v[6:7], v[160:161], 0, s[44:45]
	global_load_dwordx4 v[116:119], v[6:7], off offset:1024
	s_add_u32 s44, s72, 0xe420000
	s_addc_u32 s45, s73, 0
	v_lshl_add_u64 v[0:1], v[160:161], 0, s[44:45]
	global_load_dwordx4 v[120:123], v[0:1], off offset:1024
	s_mov_b32 m0, s101
	s_add_u32 s44, s72, 0x12400000
	s_addc_u32 s45, s73, 0
	v_lshl_add_u64 v[6:7], v[158:159], 0, s[44:45]
	global_load_lds_dwordx4 v[6:7], off offset:1024
	s_add_i32 m0, s101, 0x400
	s_add_u32 s44, s72, 0x12408000
	s_addc_u32 s45, s73, 0
	v_lshl_add_u64 v[0:1], v[158:159], 0, s[44:45]
	global_load_lds_dwordx4 v[0:1], off offset:1024
	s_and_saveexec_b64 s[24:25], s[4:5]
	s_cbranch_execz .LBB0_230
	v_add_u32_e32 v0, s36, v183
	v_ashrrev_i32_e32 v1, 31, v0
	v_lshl_add_u64 v[0:1], v[0:1], 2, s[20:21]
	global_load_dword v179, v[0:1], off

; __device__ __forceinline__ void fox_phase(LAS unsigned char* lds, int L) {
;     ...
;             if (it + 1 < NT) FOX_STORE((it + 1) & 1);
.LBB0_248:
	s_bitcmp1_b32 s43, 0
	s_cselect_b32 s3, 0x9000, 0
	v_add_u32_e32 v0, s3, v136
	s_waitcnt vmcnt(0)
	ds_write_b128 v0, v[116:119]
	ds_write_b128 v0, v[120:123] offset:9216
	s_and_saveexec_b64 s[22:23], s[4:5]
	s_cbranch_execz .LBB0_250
	v_mov_b32_e32 v1, s40
	ds_read_b32 v1, v1
	s_waitcnt lgkmcnt(0)
	v_add_f32_e32 v179, v179, v1
	v_mul_f32_e32 v0, 0xbfb8aa3b, v179
	v_bfe_u32 v1, v0, 16, 1
	v_add3_u32 v0, v0, v1, s89
	v_and_b32_e32 v1, 0xffff0000, v0
	v_fma_f32 v1, v179, s98, -v1
	v_bfe_u32 v3, v1, 16, 1
	v_add3_u32 v3, v1, v3, s89
	v_and_b32_e32 v3, 0xffff0000, v3
	v_sub_f32_e32 v1, v1, v3
	v_bfe_u32 v4, v1, 16, 1
	v_add3_u32 v1, v1, v4, s89
	v_lshrrev_b32_e32 v1, 16, v1
	v_or_b32_sdwa v0, v3, v0 dst_sel:DWORD dst_unused:UNUSED_PAD src0_sel:DWORD src1_sel:WORD_1
	v_mov_b32_e32 v3, v2
	v_add_u32_e32 v4, s3, v167
	ds_write_b128 v4, v[0:3] offset:34816
